# adds hand-interleaved K-loop for the down-projection and regenerated residual epilogues (gate quads loaded once, batched x loads, counted vmcnt) for out- and down-projection
# speedup vs baseline: 1.0635x; 1.0147x over previous
.LBB0_1093:
	v_or_b32_e32 v129, s6, v142
	v_add_u32_e32 v138, v129, v134
	v_ashrrev_i32_e32 v130, 13, v138
	v_or_b32_e32 v128, s7, v143
	v_mul_i32_i24_e32 v130, 0x1800, v130
	v_ashrrev_i32_e32 v129, 31, v128
	v_ashrrev_i32_e32 v131, 31, v130
	v_ashrrev_i32_e32 v139, 31, v138
	v_lshl_add_u64 v[140:141], v[130:131], 2, v[136:137]
	v_lshlrev_b64 v[130:131], 2, v[128:129]
	v_lshlrev_b32_e32 v134, 4, v150
	v_lshlrev_b64 v[150:151], 12, v[138:139]
	v_lshl_add_u64 v[128:129], v[140:141], 0, v[130:131]
	v_lshl_add_u64 v[140:141], s[44:45], 0, v[150:151]
	v_lshl_add_u64 v[128:129], v[128:129], 0, v[134:135]
	v_lshl_add_u64 v[140:141], v[140:141], 0, v[130:131]
	s_movk_i32 s4, 0x2000
	v_lshl_add_u64 v[152:153], v[140:141], 0, v[134:135]
	v_add_co_u32_e32 v140, vcc, s4, v128
	v_addc_co_u32_e32 v141, vcc, 0, v129, vcc
	v_readlane_b32 s6, v249, 23
	v_readlane_b32 s7, v249, 24
	s_mov_b64 s[4:5], 0x2000
	v_lshl_add_u64 v[128:129], v[128:129], 0, s[4:5]
	v_lshl_add_u64 v[150:151], s[6:7], 0, v[150:151]
	v_lshl_add_u64 v[150:151], v[150:151], 0, v[130:131]
	v_lshl_add_u64 v[150:151], v[150:151], 0, v[134:135]
	s_add_i32 s15, s15, 1
	s_mov_b64 s[4:5], 0
	s_mov_b64 s[100:101], 0x10000
	v_lshl_add_u64 v[240:241], v[152:153], 0, s[100:101]
	v_lshl_add_u64 v[242:243], v[240:241], 0, s[100:101]
	v_lshl_add_u64 v[244:245], v[242:243], 0, s[100:101]
	v_lshl_add_u64 v[246:247], v[150:151], 0, s[100:101]
	v_lshl_add_u64 v[250:251], v[246:247], 0, s[100:101]
	v_lshl_add_u64 v[252:253], v[250:251], 0, s[100:101]
	global_load_dwordx4 v[176:179], v[128:129], off
	global_load_dwordx4 v[180:183], v[128:129], off offset:64
	global_load_dwordx4 v[184:187], v[128:129], off offset:128
	global_load_dwordx4 v[188:191], v[128:129], off offset:192
	global_load_dwordx4 v[192:195], v[128:129], off offset:256
	global_load_dwordx4 v[196:199], v[128:129], off offset:320
	global_load_dwordx4 v[200:203], v[128:129], off offset:384
	global_load_dwordx4 v[204:207], v[128:129], off offset:448
	global_load_dwordx4 v[208:211], v[152:153], off
	global_load_dwordx4 v[212:215], v[152:153], off offset:64
	global_load_dwordx4 v[216:219], v[152:153], off offset:128
	global_load_dwordx4 v[220:223], v[152:153], off offset:192
	global_load_dwordx4 v[224:227], v[152:153], off offset:256
	global_load_dwordx4 v[228:231], v[152:153], off offset:320
	global_load_dwordx4 v[232:235], v[152:153], off offset:384
	global_load_dwordx4 v[236:239], v[152:153], off offset:448
	s_waitcnt vmcnt(7)
	v_pk_fma_f32 v[126:127], v[126:127], v[178:179], v[210:211]
	v_pk_fma_f32 v[124:125], v[124:125], v[176:177], v[208:209]
	global_store_dwordx4 v[150:151], v[124:127], off
	global_load_dwordx4 v[208:211], v[240:241], off
	s_waitcnt vmcnt(8)
	v_pk_fma_f32 v[122:123], v[122:123], v[182:183], v[214:215]
	v_pk_fma_f32 v[120:121], v[120:121], v[180:181], v[212:213]
	global_store_dwordx4 v[150:151], v[120:123], off offset:64
	global_load_dwordx4 v[212:215], v[240:241], off offset:64
	s_waitcnt vmcnt(9)
	v_pk_fma_f32 v[118:119], v[118:119], v[186:187], v[218:219]
	v_pk_fma_f32 v[116:117], v[116:117], v[184:185], v[216:217]
	global_store_dwordx4 v[150:151], v[116:119], off offset:128
	global_load_dwordx4 v[216:219], v[240:241], off offset:128
	s_waitcnt vmcnt(10)
	v_pk_fma_f32 v[114:115], v[114:115], v[190:191], v[222:223]
	v_pk_fma_f32 v[112:113], v[112:113], v[188:189], v[220:221]
	global_store_dwordx4 v[150:151], v[112:115], off offset:192
	global_load_dwordx4 v[220:223], v[240:241], off offset:192
	s_waitcnt vmcnt(11)
	v_pk_fma_f32 v[110:111], v[110:111], v[194:195], v[226:227]
	v_pk_fma_f32 v[108:109], v[108:109], v[192:193], v[224:225]
	global_store_dwordx4 v[150:151], v[108:111], off offset:256
	global_load_dwordx4 v[224:227], v[240:241], off offset:256
	s_waitcnt vmcnt(12)
	v_pk_fma_f32 v[106:107], v[106:107], v[198:199], v[230:231]
	v_pk_fma_f32 v[104:105], v[104:105], v[196:197], v[228:229]
	global_store_dwordx4 v[150:151], v[104:107], off offset:320
	global_load_dwordx4 v[228:231], v[240:241], off offset:320
	s_waitcnt vmcnt(13)
	v_pk_fma_f32 v[102:103], v[102:103], v[202:203], v[234:235]
	v_pk_fma_f32 v[100:101], v[100:101], v[200:201], v[232:233]
	global_store_dwordx4 v[150:151], v[100:103], off offset:384
	global_load_dwordx4 v[232:235], v[240:241], off offset:384
	s_waitcnt vmcnt(14)
	v_pk_fma_f32 v[98:99], v[98:99], v[206:207], v[238:239]
	v_pk_fma_f32 v[96:97], v[96:97], v[204:205], v[236:237]
	global_store_dwordx4 v[150:151], v[96:99], off offset:448
	global_load_dwordx4 v[236:239], v[240:241], off offset:448
	s_waitcnt vmcnt(14)
	v_pk_fma_f32 v[94:95], v[94:95], v[178:179], v[210:211]
	v_pk_fma_f32 v[92:93], v[92:93], v[176:177], v[208:209]
	global_store_dwordx4 v[246:247], v[92:95], off
	global_load_dwordx4 v[208:211], v[242:243], off
	s_waitcnt vmcnt(14)
	v_pk_fma_f32 v[90:91], v[90:91], v[182:183], v[214:215]
	v_pk_fma_f32 v[88:89], v[88:89], v[180:181], v[212:213]
	global_store_dwordx4 v[246:247], v[88:91], off offset:64
	global_load_dwordx4 v[212:215], v[242:243], off offset:64
	s_waitcnt vmcnt(14)
	v_pk_fma_f32 v[86:87], v[86:87], v[186:187], v[218:219]
	v_pk_fma_f32 v[84:85], v[84:85], v[184:185], v[216:217]
	global_store_dwordx4 v[246:247], v[84:87], off offset:128
	global_load_dwordx4 v[216:219], v[242:243], off offset:128
	s_waitcnt vmcnt(14)
	v_pk_fma_f32 v[82:83], v[82:83], v[190:191], v[222:223]
	v_pk_fma_f32 v[80:81], v[80:81], v[188:189], v[220:221]
	global_store_dwordx4 v[246:247], v[80:83], off offset:192
	global_load_dwordx4 v[220:223], v[242:243], off offset:192
	s_waitcnt vmcnt(14)
	v_pk_fma_f32 v[78:79], v[78:79], v[194:195], v[226:227]
	v_pk_fma_f32 v[76:77], v[76:77], v[192:193], v[224:225]
	global_store_dwordx4 v[246:247], v[76:79], off offset:256
	global_load_dwordx4 v[224:227], v[242:243], off offset:256
	s_waitcnt vmcnt(14)
	v_pk_fma_f32 v[74:75], v[74:75], v[198:199], v[230:231]
	v_pk_fma_f32 v[72:73], v[72:73], v[196:197], v[228:229]
	global_store_dwordx4 v[246:247], v[72:75], off offset:320
	global_load_dwordx4 v[228:231], v[242:243], off offset:320
	s_waitcnt vmcnt(14)
	v_pk_fma_f32 v[70:71], v[70:71], v[202:203], v[234:235]
	v_pk_fma_f32 v[68:69], v[68:69], v[200:201], v[232:233]
	global_store_dwordx4 v[246:247], v[68:71], off offset:384
	global_load_dwordx4 v[232:235], v[242:243], off offset:384
	s_waitcnt vmcnt(14)
	v_pk_fma_f32 v[66:67], v[66:67], v[206:207], v[238:239]
	v_pk_fma_f32 v[64:65], v[64:65], v[204:205], v[236:237]
	global_store_dwordx4 v[246:247], v[64:67], off offset:448
	global_load_dwordx4 v[236:239], v[242:243], off offset:448
	s_waitcnt vmcnt(14)
	v_pk_fma_f32 v[62:63], v[62:63], v[178:179], v[210:211]
	v_pk_fma_f32 v[60:61], v[60:61], v[176:177], v[208:209]
	global_store_dwordx4 v[250:251], v[60:63], off
	global_load_dwordx4 v[208:211], v[244:245], off
	s_waitcnt vmcnt(14)
	v_pk_fma_f32 v[58:59], v[58:59], v[182:183], v[214:215]
	v_pk_fma_f32 v[56:57], v[56:57], v[180:181], v[212:213]
	global_store_dwordx4 v[250:251], v[56:59], off offset:64
	global_load_dwordx4 v[212:215], v[244:245], off offset:64
	s_waitcnt vmcnt(14)
	v_pk_fma_f32 v[54:55], v[54:55], v[186:187], v[218:219]
	v_pk_fma_f32 v[52:53], v[52:53], v[184:185], v[216:217]
	global_store_dwordx4 v[250:251], v[52:55], off offset:128
	global_load_dwordx4 v[216:219], v[244:245], off offset:128
	s_waitcnt vmcnt(14)
	v_pk_fma_f32 v[50:51], v[50:51], v[190:191], v[222:223]
	v_pk_fma_f32 v[48:49], v[48:49], v[188:189], v[220:221]
	global_store_dwordx4 v[250:251], v[48:51], off offset:192
	global_load_dwordx4 v[220:223], v[244:245], off offset:192
	s_waitcnt vmcnt(14)
	v_pk_fma_f32 v[46:47], v[46:47], v[194:195], v[226:227]
	v_pk_fma_f32 v[44:45], v[44:45], v[192:193], v[224:225]
	global_store_dwordx4 v[250:251], v[44:47], off offset:256
	global_load_dwordx4 v[224:227], v[244:245], off offset:256
	s_waitcnt vmcnt(14)
	v_pk_fma_f32 v[42:43], v[42:43], v[198:199], v[230:231]
	v_pk_fma_f32 v[40:41], v[40:41], v[196:197], v[228:229]
	global_store_dwordx4 v[250:251], v[40:43], off offset:320
	global_load_dwordx4 v[228:231], v[244:245], off offset:320
	s_waitcnt vmcnt(14)
	v_pk_fma_f32 v[38:39], v[38:39], v[202:203], v[234:235]
	v_pk_fma_f32 v[36:37], v[36:37], v[200:201], v[232:233]
	global_store_dwordx4 v[250:251], v[36:39], off offset:384
	global_load_dwordx4 v[232:235], v[244:245], off offset:384
	s_waitcnt vmcnt(14)
	v_pk_fma_f32 v[34:35], v[34:35], v[206:207], v[238:239]
	v_pk_fma_f32 v[32:33], v[32:33], v[204:205], v[236:237]
	global_store_dwordx4 v[250:251], v[32:35], off offset:448
	global_load_dwordx4 v[236:239], v[244:245], off offset:448
	s_waitcnt vmcnt(14)
	v_pk_fma_f32 v[30:31], v[30:31], v[178:179], v[210:211]
	v_pk_fma_f32 v[28:29], v[28:29], v[176:177], v[208:209]
	global_store_dwordx4 v[252:253], v[28:31], off
	s_waitcnt vmcnt(13)
	v_pk_fma_f32 v[26:27], v[26:27], v[182:183], v[214:215]
	v_pk_fma_f32 v[24:25], v[24:25], v[180:181], v[212:213]
	global_store_dwordx4 v[252:253], v[24:27], off offset:64
	s_waitcnt vmcnt(12)
	v_pk_fma_f32 v[22:23], v[22:23], v[186:187], v[218:219]
	v_pk_fma_f32 v[20:21], v[20:21], v[184:185], v[216:217]
	global_store_dwordx4 v[252:253], v[20:23], off offset:128
	s_waitcnt vmcnt(11)
	v_pk_fma_f32 v[18:19], v[18:19], v[190:191], v[222:223]
	v_pk_fma_f32 v[16:17], v[16:17], v[188:189], v[220:221]
	global_store_dwordx4 v[252:253], v[16:19], off offset:192
	s_waitcnt vmcnt(10)
	v_pk_fma_f32 v[14:15], v[14:15], v[194:195], v[226:227]
	v_pk_fma_f32 v[12:13], v[12:13], v[192:193], v[224:225]
	global_store_dwordx4 v[252:253], v[12:15], off offset:256
	s_waitcnt vmcnt(9)
	v_pk_fma_f32 v[10:11], v[10:11], v[198:199], v[230:231]
	v_pk_fma_f32 v[8:9], v[8:9], v[196:197], v[228:229]
	global_store_dwordx4 v[252:253], v[8:11], off offset:320
	s_waitcnt vmcnt(8)
	v_pk_fma_f32 v[6:7], v[6:7], v[202:203], v[234:235]
	v_pk_fma_f32 v[4:5], v[4:5], v[200:201], v[232:233]
	global_store_dwordx4 v[252:253], v[4:7], off offset:384
	s_waitcnt vmcnt(7)
	v_pk_fma_f32 v[2:3], v[2:3], v[206:207], v[238:239]
	v_pk_fma_f32 v[0:1], v[0:1], v[204:205], v[236:237]
	global_store_dwordx4 v[252:253], v[0:3], off offset:448

.LBB0_1145:
	v_or_b32_e32 v129, s6, v142
	v_add_u32_e32 v130, v129, v134
	v_ashrrev_i32_e32 v131, 13, v130
	v_or_b32_e32 v128, s7, v143
	v_mul_i32_i24_e32 v138, 0x1800, v131
	v_ashrrev_i32_e32 v129, 31, v128
	v_ashrrev_i32_e32 v139, 31, v138
	v_lshl_add_u64 v[140:141], v[138:139], 2, v[136:137]
	v_lshlrev_b64 v[138:139], 2, v[128:129]
	v_lshl_add_u64 v[128:129], v[140:141], 0, v[138:139]
	v_lshlrev_b32_e32 v134, 4, v150
	v_ashrrev_i32_e32 v131, 31, v130
	v_readlane_b32 s6, v249, 23
	v_lshl_add_u64 v[140:141], v[128:129], 0, v[134:135]
	s_mov_b64 s[4:5], 0x5000
	v_lshlrev_b64 v[142:143], 12, v[130:131]
	v_readlane_b32 s7, v249, 24
	v_lshl_add_u64 v[128:129], v[140:141], 0, s[4:5]
	s_movk_i32 s4, 0x5000
	v_lshl_add_u64 v[142:143], s[6:7], 0, v[142:143]
	v_lshl_add_u64 v[142:143], v[142:143], 0, v[138:139]
	v_add_co_u32_e32 v140, vcc, s4, v140
	v_lshl_add_u64 v[142:143], v[142:143], 0, v[134:135]
	v_addc_co_u32_e32 v141, vcc, 0, v141, vcc
	s_add_i32 s15, s15, 1
	s_mov_b64 s[4:5], 0
	s_mov_b64 s[100:101], 0x10000
	v_lshl_add_u64 v[240:241], v[142:143], 0, s[100:101]
	v_lshl_add_u64 v[242:243], v[240:241], 0, s[100:101]
	v_lshl_add_u64 v[244:245], v[242:243], 0, s[100:101]
	global_load_dwordx4 v[176:179], v[128:129], off
	global_load_dwordx4 v[180:183], v[128:129], off offset:64
	global_load_dwordx4 v[184:187], v[128:129], off offset:128
	global_load_dwordx4 v[188:191], v[128:129], off offset:192
	global_load_dwordx4 v[192:195], v[128:129], off offset:256
	global_load_dwordx4 v[196:199], v[128:129], off offset:320
	global_load_dwordx4 v[200:203], v[128:129], off offset:384
	global_load_dwordx4 v[204:207], v[128:129], off offset:448
	global_load_dwordx4 v[208:211], v[142:143], off
	global_load_dwordx4 v[212:215], v[142:143], off offset:64
	global_load_dwordx4 v[216:219], v[142:143], off offset:128
	global_load_dwordx4 v[220:223], v[142:143], off offset:192
	global_load_dwordx4 v[224:227], v[142:143], off offset:256
	global_load_dwordx4 v[228:231], v[142:143], off offset:320
	global_load_dwordx4 v[232:235], v[142:143], off offset:384
	global_load_dwordx4 v[236:239], v[142:143], off offset:448
	s_waitcnt vmcnt(7)
	v_pk_fma_f32 v[126:127], v[126:127], v[178:179], v[210:211]
	v_pk_fma_f32 v[124:125], v[124:125], v[176:177], v[208:209]
	global_store_dwordx4 v[142:143], v[124:127], off
	global_load_dwordx4 v[208:211], v[240:241], off
	s_waitcnt vmcnt(8)
	v_pk_fma_f32 v[122:123], v[122:123], v[182:183], v[214:215]
	v_pk_fma_f32 v[120:121], v[120:121], v[180:181], v[212:213]
	global_store_dwordx4 v[142:143], v[120:123], off offset:64
	global_load_dwordx4 v[212:215], v[240:241], off offset:64
	s_waitcnt vmcnt(9)
	v_pk_fma_f32 v[118:119], v[118:119], v[186:187], v[218:219]
	v_pk_fma_f32 v[116:117], v[116:117], v[184:185], v[216:217]
	global_store_dwordx4 v[142:143], v[116:119], off offset:128
	global_load_dwordx4 v[216:219], v[240:241], off offset:128
	s_waitcnt vmcnt(10)
	v_pk_fma_f32 v[114:115], v[114:115], v[190:191], v[222:223]
	v_pk_fma_f32 v[112:113], v[112:113], v[188:189], v[220:221]
	global_store_dwordx4 v[142:143], v[112:115], off offset:192
	global_load_dwordx4 v[220:223], v[240:241], off offset:192
	s_waitcnt vmcnt(11)
	v_pk_fma_f32 v[110:111], v[110:111], v[194:195], v[226:227]
	v_pk_fma_f32 v[108:109], v[108:109], v[192:193], v[224:225]
	global_store_dwordx4 v[142:143], v[108:111], off offset:256
	global_load_dwordx4 v[224:227], v[240:241], off offset:256
	s_waitcnt vmcnt(12)
	v_pk_fma_f32 v[106:107], v[106:107], v[198:199], v[230:231]
	v_pk_fma_f32 v[104:105], v[104:105], v[196:197], v[228:229]
	global_store_dwordx4 v[142:143], v[104:107], off offset:320
	global_load_dwordx4 v[228:231], v[240:241], off offset:320
	s_waitcnt vmcnt(13)
	v_pk_fma_f32 v[102:103], v[102:103], v[202:203], v[234:235]
	v_pk_fma_f32 v[100:101], v[100:101], v[200:201], v[232:233]
	global_store_dwordx4 v[142:143], v[100:103], off offset:384
	global_load_dwordx4 v[232:235], v[240:241], off offset:384
	s_waitcnt vmcnt(14)
	v_pk_fma_f32 v[98:99], v[98:99], v[206:207], v[238:239]
	v_pk_fma_f32 v[96:97], v[96:97], v[204:205], v[236:237]
	global_store_dwordx4 v[142:143], v[96:99], off offset:448
	global_load_dwordx4 v[236:239], v[240:241], off offset:448
	s_waitcnt vmcnt(14)
	v_pk_fma_f32 v[94:95], v[94:95], v[178:179], v[210:211]
	v_pk_fma_f32 v[92:93], v[92:93], v[176:177], v[208:209]
	global_store_dwordx4 v[240:241], v[92:95], off
	global_load_dwordx4 v[208:211], v[242:243], off
	s_waitcnt vmcnt(14)
	v_pk_fma_f32 v[90:91], v[90:91], v[182:183], v[214:215]
	v_pk_fma_f32 v[88:89], v[88:89], v[180:181], v[212:213]
	global_store_dwordx4 v[240:241], v[88:91], off offset:64
	global_load_dwordx4 v[212:215], v[242:243], off offset:64
	s_waitcnt vmcnt(14)
	v_pk_fma_f32 v[86:87], v[86:87], v[186:187], v[218:219]
	v_pk_fma_f32 v[84:85], v[84:85], v[184:185], v[216:217]
	global_store_dwordx4 v[240:241], v[84:87], off offset:128
	global_load_dwordx4 v[216:219], v[242:243], off offset:128
	s_waitcnt vmcnt(14)
	v_pk_fma_f32 v[82:83], v[82:83], v[190:191], v[222:223]
	v_pk_fma_f32 v[80:81], v[80:81], v[188:189], v[220:221]
	global_store_dwordx4 v[240:241], v[80:83], off offset:192
	global_load_dwordx4 v[220:223], v[242:243], off offset:192
	s_waitcnt vmcnt(14)
	v_pk_fma_f32 v[78:79], v[78:79], v[194:195], v[226:227]
	v_pk_fma_f32 v[76:77], v[76:77], v[192:193], v[224:225]
	global_store_dwordx4 v[240:241], v[76:79], off offset:256
	global_load_dwordx4 v[224:227], v[242:243], off offset:256
	s_waitcnt vmcnt(14)
	v_pk_fma_f32 v[74:75], v[74:75], v[198:199], v[230:231]
	v_pk_fma_f32 v[72:73], v[72:73], v[196:197], v[228:229]
	global_store_dwordx4 v[240:241], v[72:75], off offset:320
	global_load_dwordx4 v[228:231], v[242:243], off offset:320
	s_waitcnt vmcnt(14)
	v_pk_fma_f32 v[70:71], v[70:71], v[202:203], v[234:235]
	v_pk_fma_f32 v[68:69], v[68:69], v[200:201], v[232:233]
	global_store_dwordx4 v[240:241], v[68:71], off offset:384
	global_load_dwordx4 v[232:235], v[242:243], off offset:384
	s_waitcnt vmcnt(14)
	v_pk_fma_f32 v[66:67], v[66:67], v[206:207], v[238:239]
	v_pk_fma_f32 v[64:65], v[64:65], v[204:205], v[236:237]
	global_store_dwordx4 v[240:241], v[64:67], off offset:448
	global_load_dwordx4 v[236:239], v[242:243], off offset:448
	s_waitcnt vmcnt(14)
	v_pk_fma_f32 v[62:63], v[62:63], v[178:179], v[210:211]
	v_pk_fma_f32 v[60:61], v[60:61], v[176:177], v[208:209]
	global_store_dwordx4 v[242:243], v[60:63], off
	global_load_dwordx4 v[208:211], v[244:245], off
	s_waitcnt vmcnt(14)
	v_pk_fma_f32 v[58:59], v[58:59], v[182:183], v[214:215]
	v_pk_fma_f32 v[56:57], v[56:57], v[180:181], v[212:213]
	global_store_dwordx4 v[242:243], v[56:59], off offset:64
	global_load_dwordx4 v[212:215], v[244:245], off offset:64
	s_waitcnt vmcnt(14)
	v_pk_fma_f32 v[54:55], v[54:55], v[186:187], v[218:219]
	v_pk_fma_f32 v[52:53], v[52:53], v[184:185], v[216:217]
	global_store_dwordx4 v[242:243], v[52:55], off offset:128
	global_load_dwordx4 v[216:219], v[244:245], off offset:128
	s_waitcnt vmcnt(14)
	v_pk_fma_f32 v[50:51], v[50:51], v[190:191], v[222:223]
	v_pk_fma_f32 v[48:49], v[48:49], v[188:189], v[220:221]
	global_store_dwordx4 v[242:243], v[48:51], off offset:192
	global_load_dwordx4 v[220:223], v[244:245], off offset:192
	s_waitcnt vmcnt(14)
	v_pk_fma_f32 v[46:47], v[46:47], v[194:195], v[226:227]
	v_pk_fma_f32 v[44:45], v[44:45], v[192:193], v[224:225]
	global_store_dwordx4 v[242:243], v[44:47], off offset:256
	global_load_dwordx4 v[224:227], v[244:245], off offset:256
	s_waitcnt vmcnt(14)
	v_pk_fma_f32 v[42:43], v[42:43], v[198:199], v[230:231]
	v_pk_fma_f32 v[40:41], v[40:41], v[196:197], v[228:229]
	global_store_dwordx4 v[242:243], v[40:43], off offset:320
	global_load_dwordx4 v[228:231], v[244:245], off offset:320
	s_waitcnt vmcnt(14)
	v_pk_fma_f32 v[38:39], v[38:39], v[202:203], v[234:235]
	v_pk_fma_f32 v[36:37], v[36:37], v[200:201], v[232:233]
	global_store_dwordx4 v[242:243], v[36:39], off offset:384
	global_load_dwordx4 v[232:235], v[244:245], off offset:384
	s_waitcnt vmcnt(14)
	v_pk_fma_f32 v[34:35], v[34:35], v[206:207], v[238:239]
	v_pk_fma_f32 v[32:33], v[32:33], v[204:205], v[236:237]
	global_store_dwordx4 v[242:243], v[32:35], off offset:448
	global_load_dwordx4 v[236:239], v[244:245], off offset:448
	s_waitcnt vmcnt(14)
	v_pk_fma_f32 v[30:31], v[30:31], v[178:179], v[210:211]
	v_pk_fma_f32 v[28:29], v[28:29], v[176:177], v[208:209]
	global_store_dwordx4 v[244:245], v[28:31], off
	s_waitcnt vmcnt(13)
	v_pk_fma_f32 v[26:27], v[26:27], v[182:183], v[214:215]
	v_pk_fma_f32 v[24:25], v[24:25], v[180:181], v[212:213]
	global_store_dwordx4 v[244:245], v[24:27], off offset:64
	s_waitcnt vmcnt(12)
	v_pk_fma_f32 v[22:23], v[22:23], v[186:187], v[218:219]
	v_pk_fma_f32 v[20:21], v[20:21], v[184:185], v[216:217]
	global_store_dwordx4 v[244:245], v[20:23], off offset:128
	s_waitcnt vmcnt(11)
	v_pk_fma_f32 v[18:19], v[18:19], v[190:191], v[222:223]
	v_pk_fma_f32 v[16:17], v[16:17], v[188:189], v[220:221]
	global_store_dwordx4 v[244:245], v[16:19], off offset:192
	s_waitcnt vmcnt(10)
	v_pk_fma_f32 v[14:15], v[14:15], v[194:195], v[226:227]
	v_pk_fma_f32 v[12:13], v[12:13], v[192:193], v[224:225]
	global_store_dwordx4 v[244:245], v[12:15], off offset:256
	s_waitcnt vmcnt(9)
	v_pk_fma_f32 v[10:11], v[10:11], v[198:199], v[230:231]
	v_pk_fma_f32 v[8:9], v[8:9], v[196:197], v[228:229]
	global_store_dwordx4 v[244:245], v[8:11], off offset:320
	s_waitcnt vmcnt(8)
	v_pk_fma_f32 v[6:7], v[6:7], v[202:203], v[234:235]
	v_pk_fma_f32 v[4:5], v[4:5], v[200:201], v[232:233]
	global_store_dwordx4 v[244:245], v[4:7], off offset:384
	s_waitcnt vmcnt(7)
	v_pk_fma_f32 v[2:3], v[2:3], v[206:207], v[238:239]
	v_pk_fma_f32 v[0:1], v[0:1], v[204:205], v[236:237]
	global_store_dwordx4 v[244:245], v[0:3], off offset:448

.LBB0_1157:
	v_add_u32_e32 v172, v153, v170
	v_add_u32_e32 v173, v153, v171
	v_add_u32_e32 v174, v169, v170
	v_add_u32_e32 v175, v169, v171
	s_mov_b64 s[100:101], 0x80
	v_lshl_add_u64 v[240:241], v[128:129], 0, s[100:101]
	s_mov_b64 s[100:101], 0x80080
	v_lshl_add_u64 v[242:243], v[128:129], 0, s[100:101]
	s_mov_b64 s[100:101], 0x100080
	v_lshl_add_u64 v[244:245], v[128:129], 0, s[100:101]
	s_mov_b64 s[100:101], 0x180080
	v_lshl_add_u64 v[246:247], v[128:129], 0, s[100:101]
	s_mov_b64 s[100:101], 0x80
	v_lshl_add_u64 v[138:139], v[130:131], 0, s[100:101]
	s_mov_b64 s[100:101], 0x80080
	v_lshl_add_u64 v[140:141], v[130:131], 0, s[100:101]
	s_mov_b64 s[100:101], 0x100080
	v_lshl_add_u64 v[250:251], v[130:131], 0, s[100:101]
	s_mov_b64 s[100:101], 0x180080
	v_lshl_add_u64 v[252:253], v[130:131], 0, s[100:101]
	v_readfirstlane_b32 s100, v144
	v_readfirstlane_b32 s101, v145
	s_nop 3
	ds_read_b128 v[176:179], v172 offset:0
	ds_read_b128 v[180:183], v172 offset:2048
	ds_read_b128 v[184:187], v172 offset:4096
	ds_read_b128 v[188:191], v172 offset:6144
	ds_read_b128 v[208:211], v174 offset:0
	ds_read_b128 v[212:215], v174 offset:2048
	ds_read_b128 v[216:219], v174 offset:4096
	ds_read_b128 v[220:223], v174 offset:6144
	s_add_u32 m0, s100, 0x8000
	s_nop 0
	global_load_lds_dwordx4 v[240:241], off
	v_lshl_add_u64 v[240:241], v[240:241], 0, s[34:35]
	s_add_u32 m0, s100, 0xa000
	s_nop 0
	global_load_lds_dwordx4 v[242:243], off
	v_lshl_add_u64 v[242:243], v[242:243], 0, s[34:35]
	s_add_u32 m0, s100, 0xc000
	s_nop 0
	global_load_lds_dwordx4 v[244:245], off
	v_lshl_add_u64 v[244:245], v[244:245], 0, s[34:35]
	s_add_u32 m0, s100, 0xe000
	s_nop 0
	global_load_lds_dwordx4 v[246:247], off
	v_lshl_add_u64 v[246:247], v[246:247], 0, s[34:35]
	s_waitcnt lgkmcnt(0)
	v_mfma_f32_16x16x32_bf16 v[124:127], v[208:211], v[176:179], v[124:127]
	ds_read_b128 v[224:227], v174 offset:8192
	v_mfma_f32_16x16x32_bf16 v[120:123], v[212:215], v[176:179], v[120:123]
	ds_read_b128 v[228:231], v174 offset:10240
	v_mfma_f32_16x16x32_bf16 v[116:119], v[216:219], v[176:179], v[116:119]
	ds_read_b128 v[232:235], v174 offset:12288
	v_mfma_f32_16x16x32_bf16 v[112:115], v[220:223], v[176:179], v[112:115]
	ds_read_b128 v[236:239], v174 offset:14336
	v_mfma_f32_16x16x32_bf16 v[92:95], v[208:211], v[180:183], v[92:95]
	s_add_u32 m0, s101, 0x8000
	v_mfma_f32_16x16x32_bf16 v[88:91], v[212:215], v[180:183], v[88:91]
	global_load_lds_dwordx4 v[138:139], off
	v_lshl_add_u64 v[138:139], v[138:139], 0, s[34:35]
	v_mfma_f32_16x16x32_bf16 v[84:87], v[216:219], v[180:183], v[84:87]
	s_add_u32 m0, s101, 0xa000
	v_mfma_f32_16x16x32_bf16 v[80:83], v[220:223], v[180:183], v[80:83]
	global_load_lds_dwordx4 v[140:141], off
	v_lshl_add_u64 v[140:141], v[140:141], 0, s[34:35]
	v_mfma_f32_16x16x32_bf16 v[60:63], v[208:211], v[184:187], v[60:63]
	s_add_u32 m0, s101, 0xc000
	v_mfma_f32_16x16x32_bf16 v[56:59], v[212:215], v[184:187], v[56:59]
	global_load_lds_dwordx4 v[250:251], off
	v_lshl_add_u64 v[250:251], v[250:251], 0, s[34:35]
	v_mfma_f32_16x16x32_bf16 v[52:55], v[216:219], v[184:187], v[52:55]
	s_add_u32 m0, s101, 0xe000
	v_mfma_f32_16x16x32_bf16 v[48:51], v[220:223], v[184:187], v[48:51]
	global_load_lds_dwordx4 v[252:253], off
	v_lshl_add_u64 v[252:253], v[252:253], 0, s[34:35]
	v_mfma_f32_16x16x32_bf16 v[28:31], v[208:211], v[188:191], v[28:31]
	v_mfma_f32_16x16x32_bf16 v[24:27], v[212:215], v[188:191], v[24:27]
	v_mfma_f32_16x16x32_bf16 v[20:23], v[216:219], v[188:191], v[20:23]
	v_mfma_f32_16x16x32_bf16 v[16:19], v[220:223], v[188:191], v[16:19]
	s_waitcnt lgkmcnt(0)
	v_mfma_f32_16x16x32_bf16 v[108:111], v[224:227], v[176:179], v[108:111]
	ds_read_b128 v[192:195], v173 offset:0
	v_mfma_f32_16x16x32_bf16 v[104:107], v[228:231], v[176:179], v[104:107]
	ds_read_b128 v[196:199], v173 offset:2048
	v_mfma_f32_16x16x32_bf16 v[100:103], v[232:235], v[176:179], v[100:103]
	ds_read_b128 v[200:203], v173 offset:4096
	v_mfma_f32_16x16x32_bf16 v[96:99], v[236:239], v[176:179], v[96:99]
	ds_read_b128 v[204:207], v173 offset:6144
	v_mfma_f32_16x16x32_bf16 v[76:79], v[224:227], v[180:183], v[76:79]
	ds_read_b128 v[208:211], v175 offset:0
	v_mfma_f32_16x16x32_bf16 v[72:75], v[228:231], v[180:183], v[72:75]
	ds_read_b128 v[212:215], v175 offset:2048
	v_mfma_f32_16x16x32_bf16 v[68:71], v[232:235], v[180:183], v[68:71]
	ds_read_b128 v[216:219], v175 offset:4096
	v_mfma_f32_16x16x32_bf16 v[64:67], v[236:239], v[180:183], v[64:67]
	ds_read_b128 v[220:223], v175 offset:6144
	v_mfma_f32_16x16x32_bf16 v[44:47], v[224:227], v[184:187], v[44:47]
	v_mfma_f32_16x16x32_bf16 v[40:43], v[228:231], v[184:187], v[40:43]
	v_mfma_f32_16x16x32_bf16 v[36:39], v[232:235], v[184:187], v[36:39]
	v_mfma_f32_16x16x32_bf16 v[32:35], v[236:239], v[184:187], v[32:35]
	v_mfma_f32_16x16x32_bf16 v[12:15], v[224:227], v[188:191], v[12:15]
	v_mfma_f32_16x16x32_bf16 v[8:11], v[228:231], v[188:191], v[8:11]
	v_mfma_f32_16x16x32_bf16 v[4:7], v[232:235], v[188:191], v[4:7]
	v_mfma_f32_16x16x32_bf16 v[0:3], v[236:239], v[188:191], v[0:3]
	s_waitcnt lgkmcnt(0)
	v_mfma_f32_16x16x32_bf16 v[124:127], v[208:211], v[192:195], v[124:127]
	ds_read_b128 v[224:227], v175 offset:8192
	v_mfma_f32_16x16x32_bf16 v[120:123], v[212:215], v[192:195], v[120:123]
	ds_read_b128 v[228:231], v175 offset:10240
	v_mfma_f32_16x16x32_bf16 v[116:119], v[216:219], v[192:195], v[116:119]
	ds_read_b128 v[232:235], v175 offset:12288
	v_mfma_f32_16x16x32_bf16 v[112:115], v[220:223], v[192:195], v[112:115]
	ds_read_b128 v[236:239], v175 offset:14336
	v_mfma_f32_16x16x32_bf16 v[92:95], v[208:211], v[196:199], v[92:95]
	v_mfma_f32_16x16x32_bf16 v[88:91], v[212:215], v[196:199], v[88:91]
	v_mfma_f32_16x16x32_bf16 v[84:87], v[216:219], v[196:199], v[84:87]
	v_mfma_f32_16x16x32_bf16 v[80:83], v[220:223], v[196:199], v[80:83]
	v_mfma_f32_16x16x32_bf16 v[60:63], v[208:211], v[200:203], v[60:63]
	v_mfma_f32_16x16x32_bf16 v[56:59], v[212:215], v[200:203], v[56:59]
	v_mfma_f32_16x16x32_bf16 v[52:55], v[216:219], v[200:203], v[52:55]
	v_mfma_f32_16x16x32_bf16 v[48:51], v[220:223], v[200:203], v[48:51]
	v_mfma_f32_16x16x32_bf16 v[28:31], v[208:211], v[204:207], v[28:31]
	v_mfma_f32_16x16x32_bf16 v[24:27], v[212:215], v[204:207], v[24:27]
	v_mfma_f32_16x16x32_bf16 v[20:23], v[216:219], v[204:207], v[20:23]
	v_mfma_f32_16x16x32_bf16 v[16:19], v[220:223], v[204:207], v[16:19]
	s_waitcnt lgkmcnt(0)
	s_waitcnt vmcnt(0)
	s_barrier
	s_mov_b32 s44, 31
.Lgemm_p10_loop:
	v_mfma_f32_16x16x32_bf16 v[108:111], v[224:227], v[192:195], v[108:111]
	ds_read_b128 v[176:179], v172 offset:32768
	v_mfma_f32_16x16x32_bf16 v[104:107], v[228:231], v[192:195], v[104:107]
	ds_read_b128 v[180:183], v172 offset:34816
	v_mfma_f32_16x16x32_bf16 v[100:103], v[232:235], v[192:195], v[100:103]
	ds_read_b128 v[184:187], v172 offset:36864
	v_mfma_f32_16x16x32_bf16 v[96:99], v[236:239], v[192:195], v[96:99]
	ds_read_b128 v[188:191], v172 offset:38912
	v_mfma_f32_16x16x32_bf16 v[76:79], v[224:227], v[196:199], v[76:79]
	ds_read_b128 v[208:211], v174 offset:32768
	v_mfma_f32_16x16x32_bf16 v[72:75], v[228:231], v[196:199], v[72:75]
	ds_read_b128 v[212:215], v174 offset:34816
	v_mfma_f32_16x16x32_bf16 v[68:71], v[232:235], v[196:199], v[68:71]
	ds_read_b128 v[216:219], v174 offset:36864
	v_mfma_f32_16x16x32_bf16 v[64:67], v[236:239], v[196:199], v[64:67]
	ds_read_b128 v[220:223], v174 offset:38912
	v_mfma_f32_16x16x32_bf16 v[44:47], v[224:227], v[200:203], v[44:47]
	s_mov_b32 m0, s100
	v_mfma_f32_16x16x32_bf16 v[40:43], v[228:231], v[200:203], v[40:43]
	global_load_lds_dwordx4 v[240:241], off
	v_lshl_add_u64 v[240:241], v[240:241], 0, s[34:35]
	v_mfma_f32_16x16x32_bf16 v[36:39], v[232:235], v[200:203], v[36:39]
	s_add_u32 m0, s100, 0x2000
	v_mfma_f32_16x16x32_bf16 v[32:35], v[236:239], v[200:203], v[32:35]
	global_load_lds_dwordx4 v[242:243], off
	v_lshl_add_u64 v[242:243], v[242:243], 0, s[34:35]
	v_mfma_f32_16x16x32_bf16 v[12:15], v[224:227], v[204:207], v[12:15]
	s_add_u32 m0, s100, 0x4000
	v_mfma_f32_16x16x32_bf16 v[8:11], v[228:231], v[204:207], v[8:11]
	global_load_lds_dwordx4 v[244:245], off
	v_lshl_add_u64 v[244:245], v[244:245], 0, s[34:35]
	v_mfma_f32_16x16x32_bf16 v[4:7], v[232:235], v[204:207], v[4:7]
	s_add_u32 m0, s100, 0x6000
	v_mfma_f32_16x16x32_bf16 v[0:3], v[236:239], v[204:207], v[0:3]
	global_load_lds_dwordx4 v[246:247], off
	v_lshl_add_u64 v[246:247], v[246:247], 0, s[34:35]
	s_waitcnt lgkmcnt(0)
	v_mfma_f32_16x16x32_bf16 v[124:127], v[208:211], v[176:179], v[124:127]
	ds_read_b128 v[224:227], v174 offset:40960
	v_mfma_f32_16x16x32_bf16 v[120:123], v[212:215], v[176:179], v[120:123]
	ds_read_b128 v[228:231], v174 offset:43008
	v_mfma_f32_16x16x32_bf16 v[116:119], v[216:219], v[176:179], v[116:119]
	ds_read_b128 v[232:235], v174 offset:45056
	v_mfma_f32_16x16x32_bf16 v[112:115], v[220:223], v[176:179], v[112:115]
	ds_read_b128 v[236:239], v174 offset:47104
	v_mfma_f32_16x16x32_bf16 v[92:95], v[208:211], v[180:183], v[92:95]
	s_mov_b32 m0, s101
	v_mfma_f32_16x16x32_bf16 v[88:91], v[212:215], v[180:183], v[88:91]
	global_load_lds_dwordx4 v[138:139], off
	v_lshl_add_u64 v[138:139], v[138:139], 0, s[34:35]
	v_mfma_f32_16x16x32_bf16 v[84:87], v[216:219], v[180:183], v[84:87]
	s_add_u32 m0, s101, 0x2000
	v_mfma_f32_16x16x32_bf16 v[80:83], v[220:223], v[180:183], v[80:83]
	global_load_lds_dwordx4 v[140:141], off
	v_lshl_add_u64 v[140:141], v[140:141], 0, s[34:35]
	v_mfma_f32_16x16x32_bf16 v[60:63], v[208:211], v[184:187], v[60:63]
	s_add_u32 m0, s101, 0x4000
	v_mfma_f32_16x16x32_bf16 v[56:59], v[212:215], v[184:187], v[56:59]
	global_load_lds_dwordx4 v[250:251], off
	v_lshl_add_u64 v[250:251], v[250:251], 0, s[34:35]
	v_mfma_f32_16x16x32_bf16 v[52:55], v[216:219], v[184:187], v[52:55]
	s_add_u32 m0, s101, 0x6000
	v_mfma_f32_16x16x32_bf16 v[48:51], v[220:223], v[184:187], v[48:51]
	global_load_lds_dwordx4 v[252:253], off
	v_lshl_add_u64 v[252:253], v[252:253], 0, s[34:35]
	v_mfma_f32_16x16x32_bf16 v[28:31], v[208:211], v[188:191], v[28:31]
	v_mfma_f32_16x16x32_bf16 v[24:27], v[212:215], v[188:191], v[24:27]
	v_mfma_f32_16x16x32_bf16 v[20:23], v[216:219], v[188:191], v[20:23]
	v_mfma_f32_16x16x32_bf16 v[16:19], v[220:223], v[188:191], v[16:19]
	s_waitcnt lgkmcnt(0)
	v_mfma_f32_16x16x32_bf16 v[108:111], v[224:227], v[176:179], v[108:111]
	ds_read_b128 v[192:195], v173 offset:32768
	v_mfma_f32_16x16x32_bf16 v[104:107], v[228:231], v[176:179], v[104:107]
	ds_read_b128 v[196:199], v173 offset:34816
	v_mfma_f32_16x16x32_bf16 v[100:103], v[232:235], v[176:179], v[100:103]
	ds_read_b128 v[200:203], v173 offset:36864
	v_mfma_f32_16x16x32_bf16 v[96:99], v[236:239], v[176:179], v[96:99]
	ds_read_b128 v[204:207], v173 offset:38912
	v_mfma_f32_16x16x32_bf16 v[76:79], v[224:227], v[180:183], v[76:79]
	ds_read_b128 v[208:211], v175 offset:32768
	v_mfma_f32_16x16x32_bf16 v[72:75], v[228:231], v[180:183], v[72:75]
	ds_read_b128 v[212:215], v175 offset:34816
	v_mfma_f32_16x16x32_bf16 v[68:71], v[232:235], v[180:183], v[68:71]
	ds_read_b128 v[216:219], v175 offset:36864
	v_mfma_f32_16x16x32_bf16 v[64:67], v[236:239], v[180:183], v[64:67]
	ds_read_b128 v[220:223], v175 offset:38912
	v_mfma_f32_16x16x32_bf16 v[44:47], v[224:227], v[184:187], v[44:47]
	v_mfma_f32_16x16x32_bf16 v[40:43], v[228:231], v[184:187], v[40:43]
	v_mfma_f32_16x16x32_bf16 v[36:39], v[232:235], v[184:187], v[36:39]
	v_mfma_f32_16x16x32_bf16 v[32:35], v[236:239], v[184:187], v[32:35]
	v_mfma_f32_16x16x32_bf16 v[12:15], v[224:227], v[188:191], v[12:15]
	v_mfma_f32_16x16x32_bf16 v[8:11], v[228:231], v[188:191], v[8:11]
	v_mfma_f32_16x16x32_bf16 v[4:7], v[232:235], v[188:191], v[4:7]
	v_mfma_f32_16x16x32_bf16 v[0:3], v[236:239], v[188:191], v[0:3]
	s_waitcnt lgkmcnt(0)
	v_mfma_f32_16x16x32_bf16 v[124:127], v[208:211], v[192:195], v[124:127]
	ds_read_b128 v[224:227], v175 offset:40960
	v_mfma_f32_16x16x32_bf16 v[120:123], v[212:215], v[192:195], v[120:123]
	ds_read_b128 v[228:231], v175 offset:43008
	v_mfma_f32_16x16x32_bf16 v[116:119], v[216:219], v[192:195], v[116:119]
	ds_read_b128 v[232:235], v175 offset:45056
	v_mfma_f32_16x16x32_bf16 v[112:115], v[220:223], v[192:195], v[112:115]
	ds_read_b128 v[236:239], v175 offset:47104
	v_mfma_f32_16x16x32_bf16 v[92:95], v[208:211], v[196:199], v[92:95]
	v_mfma_f32_16x16x32_bf16 v[88:91], v[212:215], v[196:199], v[88:91]
	v_mfma_f32_16x16x32_bf16 v[84:87], v[216:219], v[196:199], v[84:87]
	v_mfma_f32_16x16x32_bf16 v[80:83], v[220:223], v[196:199], v[80:83]
	v_mfma_f32_16x16x32_bf16 v[60:63], v[208:211], v[200:203], v[60:63]
	v_mfma_f32_16x16x32_bf16 v[56:59], v[212:215], v[200:203], v[56:59]
	v_mfma_f32_16x16x32_bf16 v[52:55], v[216:219], v[200:203], v[52:55]
	v_mfma_f32_16x16x32_bf16 v[48:51], v[220:223], v[200:203], v[48:51]
	v_mfma_f32_16x16x32_bf16 v[28:31], v[208:211], v[204:207], v[28:31]
	v_mfma_f32_16x16x32_bf16 v[24:27], v[212:215], v[204:207], v[24:27]
	v_mfma_f32_16x16x32_bf16 v[20:23], v[216:219], v[204:207], v[20:23]
	v_mfma_f32_16x16x32_bf16 v[16:19], v[220:223], v[204:207], v[16:19]
	s_waitcnt lgkmcnt(0)
	s_waitcnt vmcnt(0)
	s_barrier
	v_mfma_f32_16x16x32_bf16 v[108:111], v[224:227], v[192:195], v[108:111]
	ds_read_b128 v[176:179], v172 offset:0
	v_mfma_f32_16x16x32_bf16 v[104:107], v[228:231], v[192:195], v[104:107]
	ds_read_b128 v[180:183], v172 offset:2048
	v_mfma_f32_16x16x32_bf16 v[100:103], v[232:235], v[192:195], v[100:103]
	ds_read_b128 v[184:187], v172 offset:4096
	v_mfma_f32_16x16x32_bf16 v[96:99], v[236:239], v[192:195], v[96:99]
	ds_read_b128 v[188:191], v172 offset:6144
	v_mfma_f32_16x16x32_bf16 v[76:79], v[224:227], v[196:199], v[76:79]
	ds_read_b128 v[208:211], v174 offset:0
	v_mfma_f32_16x16x32_bf16 v[72:75], v[228:231], v[196:199], v[72:75]
	ds_read_b128 v[212:215], v174 offset:2048
	v_mfma_f32_16x16x32_bf16 v[68:71], v[232:235], v[196:199], v[68:71]
	ds_read_b128 v[216:219], v174 offset:4096
	v_mfma_f32_16x16x32_bf16 v[64:67], v[236:239], v[196:199], v[64:67]
	ds_read_b128 v[220:223], v174 offset:6144
	v_mfma_f32_16x16x32_bf16 v[44:47], v[224:227], v[200:203], v[44:47]
	s_add_u32 m0, s100, 0x8000
	v_mfma_f32_16x16x32_bf16 v[40:43], v[228:231], v[200:203], v[40:43]
	global_load_lds_dwordx4 v[240:241], off
	v_lshl_add_u64 v[240:241], v[240:241], 0, s[34:35]
	v_mfma_f32_16x16x32_bf16 v[36:39], v[232:235], v[200:203], v[36:39]
	s_add_u32 m0, s100, 0xa000
	v_mfma_f32_16x16x32_bf16 v[32:35], v[236:239], v[200:203], v[32:35]
	global_load_lds_dwordx4 v[242:243], off
	v_lshl_add_u64 v[242:243], v[242:243], 0, s[34:35]
	v_mfma_f32_16x16x32_bf16 v[12:15], v[224:227], v[204:207], v[12:15]
	s_add_u32 m0, s100, 0xc000
	v_mfma_f32_16x16x32_bf16 v[8:11], v[228:231], v[204:207], v[8:11]
	global_load_lds_dwordx4 v[244:245], off
	v_lshl_add_u64 v[244:245], v[244:245], 0, s[34:35]
	v_mfma_f32_16x16x32_bf16 v[4:7], v[232:235], v[204:207], v[4:7]
	s_add_u32 m0, s100, 0xe000
	v_mfma_f32_16x16x32_bf16 v[0:3], v[236:239], v[204:207], v[0:3]
	global_load_lds_dwordx4 v[246:247], off
	v_lshl_add_u64 v[246:247], v[246:247], 0, s[34:35]
	s_waitcnt lgkmcnt(0)
	v_mfma_f32_16x16x32_bf16 v[124:127], v[208:211], v[176:179], v[124:127]
	ds_read_b128 v[224:227], v174 offset:8192
	v_mfma_f32_16x16x32_bf16 v[120:123], v[212:215], v[176:179], v[120:123]
	ds_read_b128 v[228:231], v174 offset:10240
	v_mfma_f32_16x16x32_bf16 v[116:119], v[216:219], v[176:179], v[116:119]
	ds_read_b128 v[232:235], v174 offset:12288
	v_mfma_f32_16x16x32_bf16 v[112:115], v[220:223], v[176:179], v[112:115]
	ds_read_b128 v[236:239], v174 offset:14336
	v_mfma_f32_16x16x32_bf16 v[92:95], v[208:211], v[180:183], v[92:95]
	s_add_u32 m0, s101, 0x8000
	v_mfma_f32_16x16x32_bf16 v[88:91], v[212:215], v[180:183], v[88:91]
	global_load_lds_dwordx4 v[138:139], off
	v_lshl_add_u64 v[138:139], v[138:139], 0, s[34:35]
	v_mfma_f32_16x16x32_bf16 v[84:87], v[216:219], v[180:183], v[84:87]
	s_add_u32 m0, s101, 0xa000
	v_mfma_f32_16x16x32_bf16 v[80:83], v[220:223], v[180:183], v[80:83]
	global_load_lds_dwordx4 v[140:141], off
	v_lshl_add_u64 v[140:141], v[140:141], 0, s[34:35]
	v_mfma_f32_16x16x32_bf16 v[60:63], v[208:211], v[184:187], v[60:63]
	s_add_u32 m0, s101, 0xc000
	v_mfma_f32_16x16x32_bf16 v[56:59], v[212:215], v[184:187], v[56:59]
	global_load_lds_dwordx4 v[250:251], off
	v_lshl_add_u64 v[250:251], v[250:251], 0, s[34:35]
	v_mfma_f32_16x16x32_bf16 v[52:55], v[216:219], v[184:187], v[52:55]
	s_add_u32 m0, s101, 0xe000
	v_mfma_f32_16x16x32_bf16 v[48:51], v[220:223], v[184:187], v[48:51]
	global_load_lds_dwordx4 v[252:253], off
	v_lshl_add_u64 v[252:253], v[252:253], 0, s[34:35]
	v_mfma_f32_16x16x32_bf16 v[28:31], v[208:211], v[188:191], v[28:31]
	v_mfma_f32_16x16x32_bf16 v[24:27], v[212:215], v[188:191], v[24:27]
	v_mfma_f32_16x16x32_bf16 v[20:23], v[216:219], v[188:191], v[20:23]
	v_mfma_f32_16x16x32_bf16 v[16:19], v[220:223], v[188:191], v[16:19]
	s_waitcnt lgkmcnt(0)
	v_mfma_f32_16x16x32_bf16 v[108:111], v[224:227], v[176:179], v[108:111]
	ds_read_b128 v[192:195], v173 offset:0
	v_mfma_f32_16x16x32_bf16 v[104:107], v[228:231], v[176:179], v[104:107]
	ds_read_b128 v[196:199], v173 offset:2048
	v_mfma_f32_16x16x32_bf16 v[100:103], v[232:235], v[176:179], v[100:103]
	ds_read_b128 v[200:203], v173 offset:4096
	v_mfma_f32_16x16x32_bf16 v[96:99], v[236:239], v[176:179], v[96:99]
	ds_read_b128 v[204:207], v173 offset:6144
	v_mfma_f32_16x16x32_bf16 v[76:79], v[224:227], v[180:183], v[76:79]
	ds_read_b128 v[208:211], v175 offset:0
	v_mfma_f32_16x16x32_bf16 v[72:75], v[228:231], v[180:183], v[72:75]
	ds_read_b128 v[212:215], v175 offset:2048
	v_mfma_f32_16x16x32_bf16 v[68:71], v[232:235], v[180:183], v[68:71]
	ds_read_b128 v[216:219], v175 offset:4096
	v_mfma_f32_16x16x32_bf16 v[64:67], v[236:239], v[180:183], v[64:67]
	ds_read_b128 v[220:223], v175 offset:6144
	v_mfma_f32_16x16x32_bf16 v[44:47], v[224:227], v[184:187], v[44:47]
	v_mfma_f32_16x16x32_bf16 v[40:43], v[228:231], v[184:187], v[40:43]
	v_mfma_f32_16x16x32_bf16 v[36:39], v[232:235], v[184:187], v[36:39]
	v_mfma_f32_16x16x32_bf16 v[32:35], v[236:239], v[184:187], v[32:35]
	v_mfma_f32_16x16x32_bf16 v[12:15], v[224:227], v[188:191], v[12:15]
	v_mfma_f32_16x16x32_bf16 v[8:11], v[228:231], v[188:191], v[8:11]
	v_mfma_f32_16x16x32_bf16 v[4:7], v[232:235], v[188:191], v[4:7]
	v_mfma_f32_16x16x32_bf16 v[0:3], v[236:239], v[188:191], v[0:3]
	s_waitcnt lgkmcnt(0)
	v_mfma_f32_16x16x32_bf16 v[124:127], v[208:211], v[192:195], v[124:127]
	ds_read_b128 v[224:227], v175 offset:8192
	v_mfma_f32_16x16x32_bf16 v[120:123], v[212:215], v[192:195], v[120:123]
	ds_read_b128 v[228:231], v175 offset:10240
	v_mfma_f32_16x16x32_bf16 v[116:119], v[216:219], v[192:195], v[116:119]
	ds_read_b128 v[232:235], v175 offset:12288
	v_mfma_f32_16x16x32_bf16 v[112:115], v[220:223], v[192:195], v[112:115]
	ds_read_b128 v[236:239], v175 offset:14336
	v_mfma_f32_16x16x32_bf16 v[92:95], v[208:211], v[196:199], v[92:95]
	v_mfma_f32_16x16x32_bf16 v[88:91], v[212:215], v[196:199], v[88:91]
	v_mfma_f32_16x16x32_bf16 v[84:87], v[216:219], v[196:199], v[84:87]
	v_mfma_f32_16x16x32_bf16 v[80:83], v[220:223], v[196:199], v[80:83]
	v_mfma_f32_16x16x32_bf16 v[60:63], v[208:211], v[200:203], v[60:63]
	v_mfma_f32_16x16x32_bf16 v[56:59], v[212:215], v[200:203], v[56:59]
	v_mfma_f32_16x16x32_bf16 v[52:55], v[216:219], v[200:203], v[52:55]
	v_mfma_f32_16x16x32_bf16 v[48:51], v[220:223], v[200:203], v[48:51]
	v_mfma_f32_16x16x32_bf16 v[28:31], v[208:211], v[204:207], v[28:31]
	v_mfma_f32_16x16x32_bf16 v[24:27], v[212:215], v[204:207], v[24:27]
	v_mfma_f32_16x16x32_bf16 v[20:23], v[216:219], v[204:207], v[20:23]
	v_mfma_f32_16x16x32_bf16 v[16:19], v[220:223], v[204:207], v[16:19]
	s_waitcnt lgkmcnt(0)
	s_waitcnt vmcnt(0)
	s_barrier
	s_add_i32 s44, s44, -1
	s_cmp_lg_u32 s44, 0
	s_cbranch_scc1 .Lgemm_p10_loop
	v_mfma_f32_16x16x32_bf16 v[108:111], v[224:227], v[192:195], v[108:111]
	ds_read_b128 v[176:179], v172 offset:32768
	v_mfma_f32_16x16x32_bf16 v[104:107], v[228:231], v[192:195], v[104:107]
	ds_read_b128 v[180:183], v172 offset:34816
	v_mfma_f32_16x16x32_bf16 v[100:103], v[232:235], v[192:195], v[100:103]
	ds_read_b128 v[184:187], v172 offset:36864
	v_mfma_f32_16x16x32_bf16 v[96:99], v[236:239], v[192:195], v[96:99]
	ds_read_b128 v[188:191], v172 offset:38912
	v_mfma_f32_16x16x32_bf16 v[76:79], v[224:227], v[196:199], v[76:79]
	ds_read_b128 v[208:211], v174 offset:32768
	v_mfma_f32_16x16x32_bf16 v[72:75], v[228:231], v[196:199], v[72:75]
	ds_read_b128 v[212:215], v174 offset:34816
	v_mfma_f32_16x16x32_bf16 v[68:71], v[232:235], v[196:199], v[68:71]
	ds_read_b128 v[216:219], v174 offset:36864
	v_mfma_f32_16x16x32_bf16 v[64:67], v[236:239], v[196:199], v[64:67]
	ds_read_b128 v[220:223], v174 offset:38912
	v_mfma_f32_16x16x32_bf16 v[44:47], v[224:227], v[200:203], v[44:47]
	v_mfma_f32_16x16x32_bf16 v[40:43], v[228:231], v[200:203], v[40:43]
	v_mfma_f32_16x16x32_bf16 v[36:39], v[232:235], v[200:203], v[36:39]
	v_mfma_f32_16x16x32_bf16 v[32:35], v[236:239], v[200:203], v[32:35]
	v_mfma_f32_16x16x32_bf16 v[12:15], v[224:227], v[204:207], v[12:15]
	v_mfma_f32_16x16x32_bf16 v[8:11], v[228:231], v[204:207], v[8:11]
	v_mfma_f32_16x16x32_bf16 v[4:7], v[232:235], v[204:207], v[4:7]
	v_mfma_f32_16x16x32_bf16 v[0:3], v[236:239], v[204:207], v[0:3]
	s_waitcnt lgkmcnt(0)
	v_mfma_f32_16x16x32_bf16 v[124:127], v[208:211], v[176:179], v[124:127]
	ds_read_b128 v[224:227], v174 offset:40960
	v_mfma_f32_16x16x32_bf16 v[120:123], v[212:215], v[176:179], v[120:123]
	ds_read_b128 v[228:231], v174 offset:43008
	v_mfma_f32_16x16x32_bf16 v[116:119], v[216:219], v[176:179], v[116:119]
	ds_read_b128 v[232:235], v174 offset:45056
	v_mfma_f32_16x16x32_bf16 v[112:115], v[220:223], v[176:179], v[112:115]
	ds_read_b128 v[236:239], v174 offset:47104
	v_mfma_f32_16x16x32_bf16 v[92:95], v[208:211], v[180:183], v[92:95]
	v_mfma_f32_16x16x32_bf16 v[88:91], v[212:215], v[180:183], v[88:91]
	v_mfma_f32_16x16x32_bf16 v[84:87], v[216:219], v[180:183], v[84:87]
	v_mfma_f32_16x16x32_bf16 v[80:83], v[220:223], v[180:183], v[80:83]
	v_mfma_f32_16x16x32_bf16 v[60:63], v[208:211], v[184:187], v[60:63]
	v_mfma_f32_16x16x32_bf16 v[56:59], v[212:215], v[184:187], v[56:59]
	v_mfma_f32_16x16x32_bf16 v[52:55], v[216:219], v[184:187], v[52:55]
	v_mfma_f32_16x16x32_bf16 v[48:51], v[220:223], v[184:187], v[48:51]
	v_mfma_f32_16x16x32_bf16 v[28:31], v[208:211], v[188:191], v[28:31]
	v_mfma_f32_16x16x32_bf16 v[24:27], v[212:215], v[188:191], v[24:27]
	v_mfma_f32_16x16x32_bf16 v[20:23], v[216:219], v[188:191], v[20:23]
	v_mfma_f32_16x16x32_bf16 v[16:19], v[220:223], v[188:191], v[16:19]
	s_waitcnt lgkmcnt(0)
	v_mfma_f32_16x16x32_bf16 v[108:111], v[224:227], v[176:179], v[108:111]
	ds_read_b128 v[192:195], v173 offset:32768
	v_mfma_f32_16x16x32_bf16 v[104:107], v[228:231], v[176:179], v[104:107]
	ds_read_b128 v[196:199], v173 offset:34816
	v_mfma_f32_16x16x32_bf16 v[100:103], v[232:235], v[176:179], v[100:103]
	ds_read_b128 v[200:203], v173 offset:36864
	v_mfma_f32_16x16x32_bf16 v[96:99], v[236:239], v[176:179], v[96:99]
	ds_read_b128 v[204:207], v173 offset:38912
	v_mfma_f32_16x16x32_bf16 v[76:79], v[224:227], v[180:183], v[76:79]
	ds_read_b128 v[208:211], v175 offset:32768
	v_mfma_f32_16x16x32_bf16 v[72:75], v[228:231], v[180:183], v[72:75]
	ds_read_b128 v[212:215], v175 offset:34816
	v_mfma_f32_16x16x32_bf16 v[68:71], v[232:235], v[180:183], v[68:71]
	ds_read_b128 v[216:219], v175 offset:36864
	v_mfma_f32_16x16x32_bf16 v[64:67], v[236:239], v[180:183], v[64:67]
	ds_read_b128 v[220:223], v175 offset:38912
	v_mfma_f32_16x16x32_bf16 v[44:47], v[224:227], v[184:187], v[44:47]
	v_mfma_f32_16x16x32_bf16 v[40:43], v[228:231], v[184:187], v[40:43]
	v_mfma_f32_16x16x32_bf16 v[36:39], v[232:235], v[184:187], v[36:39]
	v_mfma_f32_16x16x32_bf16 v[32:35], v[236:239], v[184:187], v[32:35]
	v_mfma_f32_16x16x32_bf16 v[12:15], v[224:227], v[188:191], v[12:15]
	v_mfma_f32_16x16x32_bf16 v[8:11], v[228:231], v[188:191], v[8:11]
	v_mfma_f32_16x16x32_bf16 v[4:7], v[232:235], v[188:191], v[4:7]
	v_mfma_f32_16x16x32_bf16 v[0:3], v[236:239], v[188:191], v[0:3]
	s_waitcnt lgkmcnt(0)
	v_mfma_f32_16x16x32_bf16 v[124:127], v[208:211], v[192:195], v[124:127]
	ds_read_b128 v[224:227], v175 offset:40960
	v_mfma_f32_16x16x32_bf16 v[120:123], v[212:215], v[192:195], v[120:123]
	ds_read_b128 v[228:231], v175 offset:43008
	v_mfma_f32_16x16x32_bf16 v[116:119], v[216:219], v[192:195], v[116:119]
	ds_read_b128 v[232:235], v175 offset:45056
	v_mfma_f32_16x16x32_bf16 v[112:115], v[220:223], v[192:195], v[112:115]
	ds_read_b128 v[236:239], v175 offset:47104
	v_mfma_f32_16x16x32_bf16 v[92:95], v[208:211], v[196:199], v[92:95]
	v_mfma_f32_16x16x32_bf16 v[88:91], v[212:215], v[196:199], v[88:91]
	v_mfma_f32_16x16x32_bf16 v[84:87], v[216:219], v[196:199], v[84:87]
	v_mfma_f32_16x16x32_bf16 v[80:83], v[220:223], v[196:199], v[80:83]
	v_mfma_f32_16x16x32_bf16 v[60:63], v[208:211], v[200:203], v[60:63]
	v_mfma_f32_16x16x32_bf16 v[56:59], v[212:215], v[200:203], v[56:59]
	v_mfma_f32_16x16x32_bf16 v[52:55], v[216:219], v[200:203], v[52:55]
	v_mfma_f32_16x16x32_bf16 v[48:51], v[220:223], v[200:203], v[48:51]
	v_mfma_f32_16x16x32_bf16 v[28:31], v[208:211], v[204:207], v[28:31]
	v_mfma_f32_16x16x32_bf16 v[24:27], v[212:215], v[204:207], v[24:27]
	v_mfma_f32_16x16x32_bf16 v[20:23], v[216:219], v[204:207], v[20:23]
	v_mfma_f32_16x16x32_bf16 v[16:19], v[220:223], v[204:207], v[16:19]
	s_waitcnt lgkmcnt(0)
	v_mfma_f32_16x16x32_bf16 v[108:111], v[224:227], v[192:195], v[108:111]
	v_mfma_f32_16x16x32_bf16 v[104:107], v[228:231], v[192:195], v[104:107]
	v_mfma_f32_16x16x32_bf16 v[100:103], v[232:235], v[192:195], v[100:103]
	v_mfma_f32_16x16x32_bf16 v[96:99], v[236:239], v[192:195], v[96:99]
	v_mfma_f32_16x16x32_bf16 v[76:79], v[224:227], v[196:199], v[76:79]
	v_mfma_f32_16x16x32_bf16 v[72:75], v[228:231], v[196:199], v[72:75]
	v_mfma_f32_16x16x32_bf16 v[68:71], v[232:235], v[196:199], v[68:71]
	v_mfma_f32_16x16x32_bf16 v[64:67], v[236:239], v[196:199], v[64:67]
	v_mfma_f32_16x16x32_bf16 v[44:47], v[224:227], v[200:203], v[44:47]
	v_mfma_f32_16x16x32_bf16 v[40:43], v[228:231], v[200:203], v[40:43]
	v_mfma_f32_16x16x32_bf16 v[36:39], v[232:235], v[200:203], v[36:39]
	v_mfma_f32_16x16x32_bf16 v[32:35], v[236:239], v[200:203], v[32:35]
	v_mfma_f32_16x16x32_bf16 v[12:15], v[224:227], v[204:207], v[12:15]
	v_mfma_f32_16x16x32_bf16 v[8:11], v[228:231], v[204:207], v[8:11]
	v_mfma_f32_16x16x32_bf16 v[4:7], v[232:235], v[204:207], v[4:7]
	v_mfma_f32_16x16x32_bf16 v[0:3], v[236:239], v[204:207], v[0:3]
	s_nop 7
	s_nop 3
	s_branch .LBB0_1145
